# phase 4: carry blocks skip conv items (carry and conv overlap); S5-out GEMM: counted vmcnt keeps next-tile prefetch in flight across the LDS store
# speedup vs baseline: 1.0387x; 1.0053x over previous
; #define GLOAD(RA, RB, kt) { const int k_ = (kt) * 64 + lc * 8; const long ko_ = (long)(k_ >> a.segshift) * a.segstride + (k_ & segmask); \
;     _Pragma("unroll") for (int i = 0; i < 4; ++i) RA[i] = *(const u32x4*)(ap[i] + ko_); \
;     _Pragma("unroll") for (int i = 0; i < NBL; ++i) RB[i] = *(const u32x4*)(bp + (long)(32 * i) * ldb + (kt) * 64); }
; #define LSTORE(RA, RB, buf) { char* s_ = smem + (buf) * STAGE; \
;     _Pragma("unroll") for (int i = 0; i < 4; ++i) *(u32x4*)(s_ + wofs + i * 4096) = RA[i]; \
;     _Pragma("unroll") for (int i = 0; i < NBL; ++i) *(u32x4*)(s_ + ABYTES + wofs + i * 4096) = RB[i]; }
; #define BAR() { asm volatile("s_waitcnt lgkmcnt(0)" ::: "memory"); __builtin_amdgcn_s_barrier(); asm volatile("" ::: "memory"); }
; template <int WN, bool SWAP>
; DEV void gemm_core(f32x4 (&acc)[4][WN], const ASrc& a, const bf16_t* __restrict__ Bt, long ldb, int K, char* smem) {
;     ...
;   __builtin_amdgcn_sched_barrier(0);
;   GLOAD(ra0, rb0, 0); GLOAD(ra1, rb1, 1); LSTORE(ra0, rb0, 0); BAR();
; #pragma nounroll
;   for (int kt = 0; kt < nk; kt += 2) {
;     if (kt + 2 < nk) GLOAD(ra0, rb0, kt + 2);
;     COMPUTE(0);
;     LSTORE(ra1, rb1, 1);
.LBB0_123:
	v_add_u32_e32 v152, v148, v149
	ds_read_b128 v[154:157], v152 offset:16384
	ds_read_b128 v[162:165], v152 offset:18432
	ds_read_b128 v[166:169], v152 offset:20480
	ds_read_b128 v[170:173], v152 offset:22528
	v_add_u32_e32 v40, v147, v149
	ds_read_b128 v[158:161], v40
	v_add_u32_e32 v153, v148, v150
	v_add_u32_e32 v151, v147, v150
	s_cmp_ge_i32 s24, s7
	s_waitcnt lgkmcnt(0)
	v_mfma_f32_16x16x32_bf16 v[64:67], v[154:157], v[158:161], v[64:67]
	ds_read_b128 v[186:189], v153 offset:16384
	ds_read_b128 v[190:193], v153 offset:22528
	v_mfma_f32_16x16x32_bf16 v[60:63], v[162:165], v[158:161], v[60:63]
	v_mfma_f32_16x16x32_bf16 v[56:59], v[166:169], v[158:161], v[56:59]
	v_mfma_f32_16x16x32_bf16 v[52:55], v[170:173], v[158:161], v[52:55]
	ds_read_b128 v[158:161], v40 offset:2048
	s_waitcnt lgkmcnt(0)
	v_mfma_f32_16x16x32_bf16 v[48:51], v[154:157], v[158:161], v[48:51]
	v_mfma_f32_16x16x32_bf16 v[42:45], v[162:165], v[158:161], v[44:47]
	v_mfma_f32_16x16x32_bf16 v[36:39], v[166:169], v[158:161], v[36:39]
	v_mfma_f32_16x16x32_bf16 v[32:35], v[170:173], v[158:161], v[32:35]
	ds_read_b128 v[158:161], v40 offset:4096
	s_waitcnt lgkmcnt(0)
	v_mfma_f32_16x16x32_bf16 v[174:177], v[154:157], v[158:161], v[28:31]
	s_nop 2
	ds_read_b128 v[28:31], v151 offset:2048
	v_mfma_f32_16x16x32_bf16 v[178:181], v[162:165], v[158:161], v[24:27]
	v_mfma_f32_16x16x32_bf16 v[182:185], v[166:169], v[158:161], v[20:23]
	v_mfma_f32_16x16x32_bf16 v[158:161], v[170:173], v[158:161], v[16:19]
	s_nop 2
	ds_read_b128 v[16:19], v40 offset:6144
	s_waitcnt lgkmcnt(0)
	v_mfma_f32_16x16x32_bf16 v[154:157], v[154:157], v[16:19], v[12:15]
	s_nop 2
	ds_read_b128 v[12:15], v151
	v_mfma_f32_16x16x32_bf16 v[162:165], v[162:165], v[16:19], v[8:11]
	v_mfma_f32_16x16x32_bf16 v[166:169], v[166:169], v[16:19], v[4:7]
	v_mfma_f32_16x16x32_bf16 v[170:173], v[170:173], v[16:19], v[0:3]
	v_mfma_f32_16x16x32_bf16 v[16:19], v[186:189], v[28:31], v[48:51]
	s_nop 2
	ds_read_b128 v[46:49], v151 offset:4096
	s_waitcnt lgkmcnt(1)
	v_mfma_f32_16x16x32_bf16 v[0:3], v[186:189], v[12:15], v[64:67]
	s_nop 2
	ds_read_b128 v[64:67], v153 offset:18432
	s_waitcnt lgkmcnt(0)
	v_mfma_f32_16x16x32_bf16 v[4:7], v[64:67], v[12:15], v[60:63]
	s_nop 2
	ds_read_b128 v[60:63], v153 offset:20480
	v_mfma_f32_16x16x32_bf16 v[20:23], v[64:67], v[28:31], v[42:45]
	s_waitcnt lgkmcnt(0)
	v_mfma_f32_16x16x32_bf16 v[24:27], v[60:63], v[28:31], v[36:39]
	v_mfma_f32_16x16x32_bf16 v[28:31], v[190:193], v[28:31], v[32:35]
	v_mfma_f32_16x16x32_bf16 v[32:35], v[186:189], v[46:49], v[174:177]
	v_mfma_f32_16x16x32_bf16 v[36:39], v[64:67], v[46:49], v[178:181]
	v_mfma_f32_16x16x32_bf16 v[42:45], v[60:63], v[46:49], v[182:185]
	v_mfma_f32_16x16x32_bf16 v[46:49], v[190:193], v[46:49], v[158:161]
	s_nop 2
	ds_read_b128 v[158:161], v151 offset:6144
	v_mfma_f32_16x16x32_bf16 v[8:11], v[60:63], v[12:15], v[56:59]
	s_mov_b64 vcc, s[14:15]
	s_cbranch_vccz .Ls5g_lo_a
	s_waitcnt vmcnt(15)
	ds_write_b128 v146, v[92:95] offset:32768
	s_waitcnt vmcnt(14)
	ds_write_b128 v146, v[100:103] offset:36864
	s_waitcnt vmcnt(13)
	ds_write_b128 v146, v[104:107] offset:40960
	s_waitcnt vmcnt(12)
	ds_write_b128 v146, v[112:115] offset:45056
	s_waitcnt vmcnt(11)
	ds_write_b128 v146, v[116:119] offset:49152
	s_waitcnt vmcnt(10)
	ds_write_b128 v146, v[120:123] offset:53248
	s_waitcnt vmcnt(9)
	ds_write_b128 v146, v[124:127] offset:57344
	s_waitcnt vmcnt(8)
	ds_write_b128 v146, v[128:131] offset:61440
	s_branch .Ls5g_done_a
.Ls5g_lo_a:
	s_waitcnt vmcnt(7)
	ds_write_b128 v146, v[92:95] offset:32768
	s_waitcnt vmcnt(6)
	ds_write_b128 v146, v[100:103] offset:36864
	s_waitcnt vmcnt(5)
	ds_write_b128 v146, v[104:107] offset:40960
	s_waitcnt vmcnt(4)
	ds_write_b128 v146, v[112:115] offset:45056
	s_waitcnt vmcnt(3)
	ds_write_b128 v146, v[116:119] offset:49152
	s_waitcnt vmcnt(2)
	ds_write_b128 v146, v[120:123] offset:53248
	s_waitcnt vmcnt(1)
	ds_write_b128 v146, v[124:127] offset:57344
	s_waitcnt vmcnt(0)
	ds_write_b128 v146, v[128:131] offset:61440
; #define GLOAD(RA, RB, kt) { const int k_ = (kt) * 64 + lc * 8; const long ko_ = (long)(k_ >> a.segshift) * a.segstride + (k_ & segmask); \
;     _Pragma("unroll") for (int i = 0; i < 4; ++i) RA[i] = *(const u32x4*)(ap[i] + ko_); \
;     _Pragma("unroll") for (int i = 0; i < NBL; ++i) RB[i] = *(const u32x4*)(bp + (long)(32 * i) * ldb + (kt) * 64); }
; #define LSTORE(RA, RB, buf) { char* s_ = smem + (buf) * STAGE; \
;     _Pragma("unroll") for (int i = 0; i < 4; ++i) *(u32x4*)(s_ + wofs + i * 4096) = RA[i]; \
;     _Pragma("unroll") for (int i = 0; i < NBL; ++i) *(u32x4*)(s_ + ABYTES + wofs + i * 4096) = RB[i]; }
; #define BAR() { asm volatile("s_waitcnt lgkmcnt(0)" ::: "memory"); __builtin_amdgcn_s_barrier(); asm volatile("" ::: "memory"); }
; template <int WN, bool SWAP>
; DEV void gemm_core(f32x4 (&acc)[4][WN], const ASrc& a, const bf16_t* __restrict__ Bt, long ldb, int K, char* smem) {
;     ...
;   __builtin_amdgcn_sched_barrier(0);
;   GLOAD(ra0, rb0, 0); GLOAD(ra1, rb1, 1); LSTORE(ra0, rb0, 0); BAR();
; #pragma nounroll
;   for (int kt = 0; kt < nk; kt += 2) {
;     if (kt + 2 < nk) GLOAD(ra0, rb0, kt + 2);
;     COMPUTE(0);
;     LSTORE(ra1, rb1, 1);
;     BAR();
;     if (kt + 3 < nk) GLOAD(ra1, rb1, kt + 3);
;     COMPUTE(1);
.Ls5g_done_a:
	v_mfma_f32_16x16x32_bf16 v[12:15], v[190:193], v[12:15], v[52:55]
	s_waitcnt lgkmcnt(0)
	s_barrier
	s_waitcnt lgkmcnt(8)
	v_mfma_f32_16x16x32_bf16 v[50:53], v[186:189], v[158:161], v[154:157]
	v_mfma_f32_16x16x32_bf16 v[54:57], v[64:67], v[158:161], v[162:165]
	v_mfma_f32_16x16x32_bf16 v[62:65], v[60:63], v[158:161], v[166:169]
	v_mfma_f32_16x16x32_bf16 v[58:61], v[190:193], v[158:161], v[170:173]
	s_cbranch_scc1 .LBB0_125
	v_add_u32_e32 v66, s12, v145
	v_lshrrev_b32_e32 v104, 4, v66
	v_mad_u64_u32 v[66:67], s[26:27], v104, s53, v[136:137]
	v_mad_u64_u32 v[100:101], s[26:27], v104, s53, v[138:139]
	global_load_dwordx4 v[92:95], v[66:67], off
	s_nop 0
	global_load_dwordx4 v[100:103], v[100:101], off
	v_mad_u64_u32 v[66:67], s[26:27], v104, s53, v[140:141]
	v_mad_u64_u32 v[112:113], s[26:27], v104, s53, v[142:143]
	s_mov_b32 s13, s85
	global_load_dwordx4 v[104:107], v[66:67], off
	s_nop 0
	global_load_dwordx4 v[112:115], v[112:113], off
	v_lshl_add_u64 v[66:67], s[12:13], 1, v[134:135]
	v_add_co_u32_e32 v120, vcc, 0x8000, v66
	s_nop 1
	v_addc_co_u32_e32 v121, vcc, 0, v67, vcc
	v_add_co_u32_e32 v124, vcc, 0x10000, v66
	global_load_dwordx4 v[116:119], v[66:67], off
	s_nop 0
	global_load_dwordx4 v[120:123], v[120:121], off
	v_addc_co_u32_e32 v125, vcc, 0, v67, vcc
	v_add_co_u32_e32 v66, vcc, 0x18000, v66
	s_nop 1
	v_addc_co_u32_e32 v67, vcc, 0, v67, vcc
	global_load_dwordx4 v[124:127], v[124:125], off
	s_nop 0
	global_load_dwordx4 v[128:131], v[66:67], off
.LBB0_125:
	ds_read_b128 v[154:157], v152 offset:49152
	ds_read_b128 v[158:161], v40 offset:32768
	ds_read_b128 v[162:165], v152 offset:51200
	ds_read_b128 v[166:169], v152 offset:53248
	ds_read_b128 v[170:173], v152 offset:55296
	s_andn2_b64 vcc, exec, s[14:15]
	s_waitcnt lgkmcnt(3)
	v_mfma_f32_16x16x32_bf16 v[0:3], v[154:157], v[158:161], v[0:3]
	ds_read_b128 v[186:189], v153 offset:49152
	ds_read_b128 v[190:193], v153 offset:55296
	s_waitcnt lgkmcnt(4)
	v_mfma_f32_16x16x32_bf16 v[4:7], v[162:165], v[158:161], v[4:7]
	s_waitcnt lgkmcnt(3)
	v_mfma_f32_16x16x32_bf16 v[8:11], v[166:169], v[158:161], v[8:11]
	s_waitcnt lgkmcnt(2)
	v_mfma_f32_16x16x32_bf16 v[12:15], v[170:173], v[158:161], v[12:15]
	ds_read_b128 v[158:161], v40 offset:34816
	s_waitcnt lgkmcnt(0)
	v_mfma_f32_16x16x32_bf16 v[16:19], v[154:157], v[158:161], v[16:19]
	v_mfma_f32_16x16x32_bf16 v[20:23], v[162:165], v[158:161], v[20:23]
	v_mfma_f32_16x16x32_bf16 v[24:27], v[166:169], v[158:161], v[24:27]
	v_mfma_f32_16x16x32_bf16 v[28:31], v[170:173], v[158:161], v[28:31]
	ds_read_b128 v[158:161], v40 offset:36864
	s_waitcnt lgkmcnt(0)
	v_mfma_f32_16x16x32_bf16 v[174:177], v[154:157], v[158:161], v[32:35]
	s_nop 2
	ds_read_b128 v[32:35], v40 offset:38912
	v_mfma_f32_16x16x32_bf16 v[178:181], v[162:165], v[158:161], v[36:39]
	v_mfma_f32_16x16x32_bf16 v[182:185], v[166:169], v[158:161], v[42:45]
	v_mfma_f32_16x16x32_bf16 v[158:161], v[170:173], v[158:161], v[46:49]
	s_waitcnt lgkmcnt(0)
	v_mfma_f32_16x16x32_bf16 v[154:157], v[154:157], v[32:35], v[50:53]
	v_mfma_f32_16x16x32_bf16 v[162:165], v[162:165], v[32:35], v[54:57]
	v_mfma_f32_16x16x32_bf16 v[166:169], v[166:169], v[32:35], v[62:65]
	v_mfma_f32_16x16x32_bf16 v[170:173], v[170:173], v[32:35], v[58:61]
	ds_read_b128 v[32:35], v151 offset:32768
	s_waitcnt lgkmcnt(0)
	v_mfma_f32_16x16x32_bf16 v[64:67], v[186:189], v[32:35], v[0:3]
	s_nop 2
	ds_read_b128 v[0:3], v153 offset:51200
	s_waitcnt lgkmcnt(0)
	v_mfma_f32_16x16x32_bf16 v[60:63], v[0:3], v[32:35], v[4:7]
	s_nop 2
	ds_read_b128 v[4:7], v153 offset:53248
	s_waitcnt lgkmcnt(0)
	v_mfma_f32_16x16x32_bf16 v[56:59], v[4:7], v[32:35], v[8:11]
	s_nop 2
	ds_read_b128 v[8:11], v151 offset:34816
	v_mfma_f32_16x16x32_bf16 v[52:55], v[190:193], v[32:35], v[12:15]
	s_waitcnt lgkmcnt(0)
	v_mfma_f32_16x16x32_bf16 v[48:51], v[186:189], v[8:11], v[16:19]
	v_mfma_f32_16x16x32_bf16 v[44:47], v[0:3], v[8:11], v[20:23]
	v_mfma_f32_16x16x32_bf16 v[36:39], v[4:7], v[8:11], v[24:27]
	v_mfma_f32_16x16x32_bf16 v[32:35], v[190:193], v[8:11], v[28:31]
	ds_read_b128 v[8:11], v151 offset:36864
	s_waitcnt lgkmcnt(0)
	v_mfma_f32_16x16x32_bf16 v[16:19], v[190:193], v[8:11], v[158:161]
	s_nop 2
	ds_read_b128 v[158:161], v151 offset:38912
	v_mfma_f32_16x16x32_bf16 v[28:31], v[186:189], v[8:11], v[174:177]
	v_mfma_f32_16x16x32_bf16 v[24:27], v[0:3], v[8:11], v[178:181]
	v_mfma_f32_16x16x32_bf16 v[20:23], v[4:7], v[8:11], v[182:185]
	s_waitcnt lgkmcnt(0)
	v_mfma_f32_16x16x32_bf16 v[12:15], v[186:189], v[158:161], v[154:157]
	v_mfma_f32_16x16x32_bf16 v[8:11], v[0:3], v[158:161], v[162:165]
	v_mfma_f32_16x16x32_bf16 v[4:7], v[4:7], v[158:161], v[166:169]
	v_mfma_f32_16x16x32_bf16 v[0:3], v[190:193], v[158:161], v[170:173]
	s_cbranch_vccnz .LBB0_120
	s_cmp_ge_i32 s24, s7
	s_cbranch_scc1 .Ls5g_w0_a
	s_waitcnt vmcnt(8)
	s_branch .Ls5g_st_a

; #define LSTORE(RA, RB, buf) { char* s_ = smem + (buf) * STAGE; \
;     _Pragma("unroll") for (int i = 0; i < 4; ++i) *(u32x4*)(s_ + wofs + i * 4096) = RA[i]; \
;     _Pragma("unroll") for (int i = 0; i < NBL; ++i) *(u32x4*)(s_ + ABYTES + wofs + i * 4096) = RB[i]; }
; #define BAR() { asm volatile("s_waitcnt lgkmcnt(0)" ::: "memory"); __builtin_amdgcn_s_barrier(); asm volatile("" ::: "memory"); }
; template <int WN, bool SWAP>
; DEV void gemm_core(f32x4 (&acc)[4][WN], const ASrc& a, const bf16_t* __restrict__ Bt, long ldb, int K, char* smem) {
;     ...
;     if (kt + 2 < nk) LSTORE(ra0, rb0, 0);
;     BAR();
.Ls5g_st_a:
	ds_write_b128 v146, v[68:71]
	ds_write_b128 v146, v[72:75] offset:4096
	ds_write_b128 v146, v[76:79] offset:8192
	ds_write_b128 v146, v[80:83] offset:12288
	ds_write_b128 v146, v[84:87] offset:16384
	ds_write_b128 v146, v[88:91] offset:20480
	ds_write_b128 v146, v[96:99] offset:24576
	ds_write_b128 v146, v[108:111] offset:28672
	s_branch .LBB0_120

; #define GLOAD(RA, RB, kt) { const int k_ = (kt) * 64 + lc * 8; const long ko_ = (long)(k_ >> a.segshift) * a.segstride + (k_ & segmask); \
;     _Pragma("unroll") for (int i = 0; i < 4; ++i) RA[i] = *(const u32x4*)(ap[i] + ko_); \
;     _Pragma("unroll") for (int i = 0; i < NBL; ++i) RB[i] = *(const u32x4*)(bp + (long)(32 * i) * ldb + (kt) * 64); }
; #define LSTORE(RA, RB, buf) { char* s_ = smem + (buf) * STAGE; \
;     _Pragma("unroll") for (int i = 0; i < 4; ++i) *(u32x4*)(s_ + wofs + i * 4096) = RA[i]; \
;     _Pragma("unroll") for (int i = 0; i < NBL; ++i) *(u32x4*)(s_ + ABYTES + wofs + i * 4096) = RB[i]; }
; #define BAR() { asm volatile("s_waitcnt lgkmcnt(0)" ::: "memory"); __builtin_amdgcn_s_barrier(); asm volatile("" ::: "memory"); }
; template <int WN, bool SWAP>
; DEV void gemm_core(f32x4 (&acc)[4][WN], const ASrc& a, const bf16_t* __restrict__ Bt, long ldb, int K, char* smem) {
;     ...
;   __builtin_amdgcn_sched_barrier(0);
;   GLOAD(ra0, rb0, 0); GLOAD(ra1, rb1, 1); LSTORE(ra0, rb0, 0); BAR();
; #pragma nounroll
;   for (int kt = 0; kt < nk; kt += 2) {
;     if (kt + 2 < nk) GLOAD(ra0, rb0, kt + 2);
;     COMPUTE(0);
;     LSTORE(ra1, rb1, 1);
.LBB0_133:
	v_add_u32_e32 v153, v148, v149
	ds_read_b128 v[154:157], v153 offset:16384
	ds_read_b128 v[162:165], v153 offset:18432
	ds_read_b128 v[166:169], v153 offset:20480
	ds_read_b128 v[170:173], v153 offset:22528
	v_add_u32_e32 v151, v147, v149
	ds_read_b128 v[158:161], v151
	v_add_u32_e32 v152, v147, v150
	s_cmp_ge_i32 s13, s12
	s_waitcnt lgkmcnt(0)
	v_mfma_f32_16x16x32_bf16 v[64:67], v[154:157], v[158:161], v[64:67]
	v_mfma_f32_16x16x32_bf16 v[60:63], v[162:165], v[158:161], v[60:63]
	v_mfma_f32_16x16x32_bf16 v[56:59], v[166:169], v[158:161], v[56:59]
	v_mfma_f32_16x16x32_bf16 v[52:55], v[170:173], v[158:161], v[52:55]
	ds_read_b128 v[158:161], v151 offset:2048
	s_waitcnt lgkmcnt(0)
	v_mfma_f32_16x16x32_bf16 v[48:51], v[154:157], v[158:161], v[48:51]
	v_mfma_f32_16x16x32_bf16 v[42:45], v[162:165], v[158:161], v[44:47]
	v_mfma_f32_16x16x32_bf16 v[36:39], v[166:169], v[158:161], v[36:39]
	v_mfma_f32_16x16x32_bf16 v[32:35], v[170:173], v[158:161], v[32:35]
	ds_read_b128 v[158:161], v151 offset:4096
	s_waitcnt lgkmcnt(0)
	v_mfma_f32_16x16x32_bf16 v[174:177], v[154:157], v[158:161], v[28:31]
	s_nop 2
	ds_read_b128 v[28:31], v152 offset:2048
	v_mfma_f32_16x16x32_bf16 v[178:181], v[162:165], v[158:161], v[24:27]
	v_mfma_f32_16x16x32_bf16 v[182:185], v[166:169], v[158:161], v[20:23]
	v_mfma_f32_16x16x32_bf16 v[158:161], v[170:173], v[158:161], v[16:19]
	s_nop 2
	ds_read_b128 v[16:19], v151 offset:6144
	s_waitcnt lgkmcnt(0)
	v_mfma_f32_16x16x32_bf16 v[186:189], v[154:157], v[16:19], v[12:15]
	v_add_u32_e32 v154, v148, v150
	ds_read_b128 v[190:193], v154 offset:16384
	ds_read_b128 v[194:197], v154 offset:22528
	ds_read_b128 v[12:15], v152
	v_mfma_f32_16x16x32_bf16 v[162:165], v[162:165], v[16:19], v[8:11]
	v_mfma_f32_16x16x32_bf16 v[166:169], v[166:169], v[16:19], v[4:7]
	v_mfma_f32_16x16x32_bf16 v[170:173], v[170:173], v[16:19], v[0:3]
	s_waitcnt lgkmcnt(2)
	v_mfma_f32_16x16x32_bf16 v[16:19], v[190:193], v[28:31], v[48:51]
	s_nop 2
	ds_read_b128 v[46:49], v152 offset:4096
	s_waitcnt lgkmcnt(1)
	v_mfma_f32_16x16x32_bf16 v[0:3], v[190:193], v[12:15], v[64:67]
	s_nop 2
	ds_read_b128 v[64:67], v154 offset:18432
	s_waitcnt lgkmcnt(0)
	v_mfma_f32_16x16x32_bf16 v[4:7], v[64:67], v[12:15], v[60:63]
	s_nop 2
	ds_read_b128 v[60:63], v154 offset:20480
	v_mfma_f32_16x16x32_bf16 v[20:23], v[64:67], v[28:31], v[42:45]
	s_waitcnt lgkmcnt(0)
	v_mfma_f32_16x16x32_bf16 v[24:27], v[60:63], v[28:31], v[36:39]
	v_mfma_f32_16x16x32_bf16 v[28:31], v[194:197], v[28:31], v[32:35]
	v_mfma_f32_16x16x32_bf16 v[32:35], v[190:193], v[46:49], v[174:177]
	v_mfma_f32_16x16x32_bf16 v[36:39], v[64:67], v[46:49], v[178:181]
	v_mfma_f32_16x16x32_bf16 v[42:45], v[60:63], v[46:49], v[182:185]
	v_mfma_f32_16x16x32_bf16 v[46:49], v[194:197], v[46:49], v[158:161]
	s_nop 2
	ds_read_b128 v[156:159], v152 offset:6144
	v_mfma_f32_16x16x32_bf16 v[8:11], v[60:63], v[12:15], v[56:59]
	s_mov_b64 vcc, s[8:9]
	s_cbranch_vccz .Ls5g_lo_b
	s_waitcnt vmcnt(15)
	ds_write_b128 v146, v[92:95] offset:32768
	s_waitcnt vmcnt(14)
	ds_write_b128 v146, v[96:99] offset:36864
	s_waitcnt vmcnt(13)
	ds_write_b128 v146, v[100:103] offset:40960
	s_waitcnt vmcnt(12)
	ds_write_b128 v146, v[104:107] offset:45056
	s_waitcnt vmcnt(11)
	ds_write_b128 v146, v[116:119] offset:49152
	s_waitcnt vmcnt(10)
	ds_write_b128 v146, v[120:123] offset:53248
	s_waitcnt vmcnt(9)
	ds_write_b128 v146, v[124:127] offset:57344
	s_waitcnt vmcnt(8)
	ds_write_b128 v146, v[128:131] offset:61440
	s_branch .Ls5g_done_b
.Ls5g_lo_b:
	s_waitcnt vmcnt(7)
	ds_write_b128 v146, v[92:95] offset:32768
	s_waitcnt vmcnt(6)
	ds_write_b128 v146, v[96:99] offset:36864
	s_waitcnt vmcnt(5)
	ds_write_b128 v146, v[100:103] offset:40960
	s_waitcnt vmcnt(4)
	ds_write_b128 v146, v[104:107] offset:45056
	s_waitcnt vmcnt(3)
	ds_write_b128 v146, v[116:119] offset:49152
	s_waitcnt vmcnt(2)
	ds_write_b128 v146, v[120:123] offset:53248
	s_waitcnt vmcnt(1)
	ds_write_b128 v146, v[124:127] offset:57344
	s_waitcnt vmcnt(0)
	ds_write_b128 v146, v[128:131] offset:61440
; #define GLOAD(RA, RB, kt) { const int k_ = (kt) * 64 + lc * 8; const long ko_ = (long)(k_ >> a.segshift) * a.segstride + (k_ & segmask); \
;     _Pragma("unroll") for (int i = 0; i < 4; ++i) RA[i] = *(const u32x4*)(ap[i] + ko_); \
;     _Pragma("unroll") for (int i = 0; i < NBL; ++i) RB[i] = *(const u32x4*)(bp + (long)(32 * i) * ldb + (kt) * 64); }
; #define LSTORE(RA, RB, buf) { char* s_ = smem + (buf) * STAGE; \
;     _Pragma("unroll") for (int i = 0; i < 4; ++i) *(u32x4*)(s_ + wofs + i * 4096) = RA[i]; \
;     _Pragma("unroll") for (int i = 0; i < NBL; ++i) *(u32x4*)(s_ + ABYTES + wofs + i * 4096) = RB[i]; }
; #define BAR() { asm volatile("s_waitcnt lgkmcnt(0)" ::: "memory"); __builtin_amdgcn_s_barrier(); asm volatile("" ::: "memory"); }
; template <int WN, bool SWAP>
; DEV void gemm_core(f32x4 (&acc)[4][WN], const ASrc& a, const bf16_t* __restrict__ Bt, long ldb, int K, char* smem) {
;     ...
;   __builtin_amdgcn_sched_barrier(0);
;   GLOAD(ra0, rb0, 0); GLOAD(ra1, rb1, 1); LSTORE(ra0, rb0, 0); BAR();
; #pragma nounroll
;   for (int kt = 0; kt < nk; kt += 2) {
;     if (kt + 2 < nk) GLOAD(ra0, rb0, kt + 2);
;     COMPUTE(0);
;     LSTORE(ra1, rb1, 1);
;     BAR();
;     if (kt + 3 < nk) GLOAD(ra1, rb1, kt + 3);
;     COMPUTE(1);
.Ls5g_done_b:
	v_mfma_f32_16x16x32_bf16 v[12:15], v[194:197], v[12:15], v[52:55]
	s_waitcnt lgkmcnt(0)
	s_barrier
	s_waitcnt lgkmcnt(8)
	v_mfma_f32_16x16x32_bf16 v[50:53], v[190:193], v[156:159], v[186:189]
	v_mfma_f32_16x16x32_bf16 v[54:57], v[64:67], v[156:159], v[162:165]
	v_mfma_f32_16x16x32_bf16 v[62:65], v[60:63], v[156:159], v[166:169]
	v_mfma_f32_16x16x32_bf16 v[58:61], v[194:197], v[156:159], v[170:173]
	s_cbranch_scc1 .LBB0_135
	s_and_b32 s7, s6, 0x3fffffc0
	v_or_b32_e32 v40, s7, v145
	v_lshlrev_b32_e32 v40, 1, v40
	v_lshl_add_u64 v[66:67], v[134:135], 0, v[40:41]
	v_lshl_add_u64 v[96:97], v[136:137], 0, v[40:41]
	global_load_dwordx4 v[92:95], v[66:67], off
	s_nop 0
	global_load_dwordx4 v[96:99], v[96:97], off
	v_lshl_add_u64 v[66:67], v[138:139], 0, v[40:41]
	v_lshl_add_u64 v[104:105], v[140:141], 0, v[40:41]
	s_mov_b32 s7, s85
	global_load_dwordx4 v[100:103], v[66:67], off
	s_nop 0
	global_load_dwordx4 v[104:107], v[104:105], off
	v_lshl_add_u64 v[66:67], s[6:7], 1, v[142:143]
	v_add_co_u32_e32 v120, vcc, 0x4000, v66
	s_nop 1
	v_addc_co_u32_e32 v121, vcc, 0, v67, vcc
	v_add_co_u32_e32 v124, vcc, 0x8000, v66
	global_load_dwordx4 v[116:119], v[66:67], off
	s_nop 0
	global_load_dwordx4 v[120:123], v[120:121], off
	v_addc_co_u32_e32 v125, vcc, 0, v67, vcc
	v_add_co_u32_e32 v66, vcc, 0xc000, v66
	s_nop 1
	v_addc_co_u32_e32 v67, vcc, 0, v67, vcc
	global_load_dwordx4 v[124:127], v[124:125], off
	s_nop 0
	global_load_dwordx4 v[128:131], v[66:67], off
.LBB0_135:
	ds_read_b128 v[156:159], v153 offset:49152
	ds_read_b128 v[160:163], v151 offset:32768
	ds_read_b128 v[164:167], v153 offset:51200
	ds_read_b128 v[168:171], v153 offset:53248
	ds_read_b128 v[172:175], v153 offset:55296
	s_andn2_b64 vcc, exec, s[8:9]
	s_waitcnt lgkmcnt(3)
	v_mfma_f32_16x16x32_bf16 v[0:3], v[156:159], v[160:163], v[0:3]
	ds_read_b128 v[188:191], v154 offset:49152
	ds_read_b128 v[192:195], v154 offset:55296
	s_waitcnt lgkmcnt(4)
	v_mfma_f32_16x16x32_bf16 v[4:7], v[164:167], v[160:163], v[4:7]
	s_waitcnt lgkmcnt(3)
	v_mfma_f32_16x16x32_bf16 v[8:11], v[168:171], v[160:163], v[8:11]
	s_waitcnt lgkmcnt(2)
	v_mfma_f32_16x16x32_bf16 v[12:15], v[172:175], v[160:163], v[12:15]
	ds_read_b128 v[160:163], v151 offset:34816
	s_waitcnt lgkmcnt(0)
	v_mfma_f32_16x16x32_bf16 v[16:19], v[156:159], v[160:163], v[16:19]
	v_mfma_f32_16x16x32_bf16 v[20:23], v[164:167], v[160:163], v[20:23]
	v_mfma_f32_16x16x32_bf16 v[24:27], v[168:171], v[160:163], v[24:27]
	v_mfma_f32_16x16x32_bf16 v[28:31], v[172:175], v[160:163], v[28:31]
	ds_read_b128 v[160:163], v151 offset:36864
	s_waitcnt lgkmcnt(0)
	v_mfma_f32_16x16x32_bf16 v[176:179], v[156:159], v[160:163], v[32:35]
	s_nop 2
	ds_read_b128 v[32:35], v151 offset:38912
	v_mfma_f32_16x16x32_bf16 v[180:183], v[164:167], v[160:163], v[36:39]
	v_mfma_f32_16x16x32_bf16 v[184:187], v[168:171], v[160:163], v[42:45]
	v_mfma_f32_16x16x32_bf16 v[160:163], v[172:175], v[160:163], v[46:49]
	s_waitcnt lgkmcnt(0)
	v_mfma_f32_16x16x32_bf16 v[156:159], v[156:159], v[32:35], v[50:53]
	v_mfma_f32_16x16x32_bf16 v[164:167], v[164:167], v[32:35], v[54:57]
	v_mfma_f32_16x16x32_bf16 v[168:171], v[168:171], v[32:35], v[62:65]
	v_mfma_f32_16x16x32_bf16 v[172:175], v[172:175], v[32:35], v[58:61]
	ds_read_b128 v[32:35], v152 offset:32768
	s_waitcnt lgkmcnt(0)
	v_mfma_f32_16x16x32_bf16 v[64:67], v[188:191], v[32:35], v[0:3]
	s_nop 2
	ds_read_b128 v[0:3], v154 offset:51200
	s_waitcnt lgkmcnt(0)
	v_mfma_f32_16x16x32_bf16 v[60:63], v[0:3], v[32:35], v[4:7]
	s_nop 2
	ds_read_b128 v[4:7], v154 offset:53248
	s_waitcnt lgkmcnt(0)
	v_mfma_f32_16x16x32_bf16 v[56:59], v[4:7], v[32:35], v[8:11]
	s_nop 2
	ds_read_b128 v[8:11], v152 offset:34816
	v_mfma_f32_16x16x32_bf16 v[52:55], v[192:195], v[32:35], v[12:15]
	s_waitcnt lgkmcnt(0)
	v_mfma_f32_16x16x32_bf16 v[48:51], v[188:191], v[8:11], v[16:19]
	v_mfma_f32_16x16x32_bf16 v[44:47], v[0:3], v[8:11], v[20:23]
	v_mfma_f32_16x16x32_bf16 v[36:39], v[4:7], v[8:11], v[24:27]
	v_mfma_f32_16x16x32_bf16 v[32:35], v[192:195], v[8:11], v[28:31]
	ds_read_b128 v[8:11], v152 offset:36864
	ds_read_b128 v[152:155], v152 offset:38912
	s_waitcnt lgkmcnt(1)
	v_mfma_f32_16x16x32_bf16 v[28:31], v[188:191], v[8:11], v[176:179]
	v_mfma_f32_16x16x32_bf16 v[24:27], v[0:3], v[8:11], v[180:183]
	v_mfma_f32_16x16x32_bf16 v[20:23], v[4:7], v[8:11], v[184:187]
	v_mfma_f32_16x16x32_bf16 v[16:19], v[192:195], v[8:11], v[160:163]
	s_waitcnt lgkmcnt(0)
	v_mfma_f32_16x16x32_bf16 v[12:15], v[188:191], v[152:155], v[156:159]
	v_mfma_f32_16x16x32_bf16 v[8:11], v[0:3], v[152:155], v[164:167]
	v_mfma_f32_16x16x32_bf16 v[4:7], v[4:7], v[152:155], v[168:171]
	v_mfma_f32_16x16x32_bf16 v[0:3], v[192:195], v[152:155], v[172:175]
	s_cbranch_vccnz .LBB0_130
	s_cmp_ge_i32 s13, s12
	s_cbranch_scc1 .Ls5g_w0_b
	s_waitcnt vmcnt(8)
	s_branch .Ls5g_st_b

; #define LSTORE(RA, RB, buf) { char* s_ = smem + (buf) * STAGE; \
;     _Pragma("unroll") for (int i = 0; i < 4; ++i) *(u32x4*)(s_ + wofs + i * 4096) = RA[i]; \
;     _Pragma("unroll") for (int i = 0; i < NBL; ++i) *(u32x4*)(s_ + ABYTES + wofs + i * 4096) = RB[i]; }
; #define BAR() { asm volatile("s_waitcnt lgkmcnt(0)" ::: "memory"); __builtin_amdgcn_s_barrier(); asm volatile("" ::: "memory"); }
; template <int WN, bool SWAP>
; DEV void gemm_core(f32x4 (&acc)[4][WN], const ASrc& a, const bf16_t* __restrict__ Bt, long ldb, int K, char* smem) {
;     ...
;     if (kt + 2 < nk) LSTORE(ra0, rb0, 0);
;     BAR();
.Ls5g_st_b:
	ds_write_b128 v146, v[68:71]
	ds_write_b128 v146, v[72:75] offset:4096
	ds_write_b128 v146, v[76:79] offset:8192
	ds_write_b128 v146, v[80:83] offset:12288
	ds_write_b128 v146, v[84:87] offset:16384
	ds_write_b128 v146, v[88:91] offset:20480
	ds_write_b128 v146, v[108:111] offset:24576
	ds_write_b128 v146, v[112:115] offset:28672
	s_branch .LBB0_130

; DEV int vbid() { return (int)blockIdx.x * 2 + vbsel(); }
; DEV int vgrid() { return (int)gridDim.x * 2; }
; DEV unsigned pk_bf16(float lo, float hi) { unsigned r; asm("v_cvt_pk_bf16_f32 %0, %1, %2" : "=v"(r) : "v"(lo), "v"(hi)); return r; }
; DEV void ph_carry(const P& p, int l, bool need) {
;     ...
;   {
;     const int Mc = need ? MALL : MLAT;
;     const int ch = (tid & 63) * 8, rsub = tid >> 6;
;     const float* cw = p.conv_w + (size_t)l * 3 * 512 + ch;
;     float w0[8], w1[8], w2[8];
; #pragma unroll
;     for (int e = 0; e < 8; ++e) { w0[e] = cw[e]; w1[e] = cw[512 + e]; w2[e] = cw[1024 + e]; }
;     for (int it = vbid(); it < Mc / 32; it += vgrid()) {
;       const int rbase = it * 32 + rsub * 8;
;       float up[8], uc[8], un[8];
;       auto loadu = [&](int row, bool valid, float (&u)[8]) {
;         if (valid) {
;           const u32x4 c = *(const u32x4*)(Z + (size_t)row * LDZ + ZCC + ch), x = *(const u32x4*)(Z + (size_t)row * LDZ + ZCX + ch);
;           u[0] = bflo(c.x) * bflo(x.x); u[1] = bfhi(c.x) * bfhi(x.x); u[2] = bflo(c.y) * bflo(x.y); u[3] = bfhi(c.y) * bfhi(x.y);
;           u[4] = bflo(c.z) * bflo(x.z); u[5] = bfhi(c.z) * bfhi(x.z); u[6] = bflo(c.w) * bflo(x.w); u[7] = bfhi(c.w) * bfhi(x.w);
;         } else {
; #pragma unroll
;           for (int e = 0; e < 8; ++e) u[e] = 0.f;
;         }
;       };
;       auto tpos = [&](int row, int& t, int& len) { if (row < MLAT) { t = row & 4095; len = 4096; } else { t = (row - MLAT) & 255; len = 256; } };
;       int t0, len0; tpos(rbase, t0, len0);
;       loadu(rbase - 1, t0 > 0, up); loadu(rbase, true, uc);
; #pragma unroll
;       for (int rr = 0; rr < 8; ++rr) {
;         const int row = rbase + rr; int t, len; tpos(row, t, len);
;         loadu(row + 1, t < len - 1, un);
;         const u32x4 zb = *(const u32x4*)(Z + (size_t)row * LDZ + ZCB + ch);
;         float y[8];
; #pragma unroll
;         for (int e = 0; e < 8; ++e) y[e] = w0[e] * up[e] + w1[e] * uc[e] + w2[e] * un[e];
;         u32x4 o;
;         o.x = pk_bf16(bflo(zb.x) * y[0], bfhi(zb.x) * y[1]); o.y = pk_bf16(bflo(zb.y) * y[2], bfhi(zb.y) * y[3]);
;         o.z = pk_bf16(bflo(zb.z) * y[4], bfhi(zb.z) * y[5]); o.w = pk_bf16(bflo(zb.w) * y[6], bfhi(zb.w) * y[7]);
;         *(u32x4*)(Z + (size_t)row * LDZ + ZCV + ch) = o;
; #pragma unroll
;         for (int e = 0; e < 8; ++e) { up[e] = uc[e]; uc[e] = un[e]; }
;       }
;     }
.LBB0_308:
	v_readfirstlane_b32 s2, v201
	s_lshr_b32 s3, s2, 8
	v_readlane_b32 s2, v253, 2
	s_add_i32 s2, s3, s2
	s_movk_i32 s8, 0x80
	s_cmpk_gt_i32 s91, 0x100
	s_cselect_b32 s8, s8, 0
	s_cmp_lt_i32 s2, s8
	s_cbranch_scc1 .LBB0_319
	s_sub_i32 s2, s2, s8
	s_sub_i32 s9, s91, s8
	s_lshl_b32 s8, s8, 5
	s_cmp_lt_i32 s2, s13
	s_cbranch_scc0 .LBB0_319
	v_lshlrev_b32_e32 v0, 3, v24
	v_readlane_b32 s6, v254, 63
	v_and_b32_e32 v25, 0x1f8, v0
	v_readlane_b32 s7, v255, 0
	s_waitcnt lgkmcnt(0)
	s_add_u32 s4, s4, s6
	s_addc_u32 s5, s5, s7
	v_lshlrev_b32_e32 v40, 2, v25
	global_load_dwordx4 v[0:3], v40, s[4:5] offset:16
	global_load_dwordx4 v[4:7], v40, s[4:5]
	global_load_dwordx4 v[8:11], v40, s[4:5] offset:2064
	global_load_dwordx4 v[12:15], v40, s[4:5] offset:2048
	v_lshl_add_u64 v[20:21], s[4:5], 0, v[40:41]
	s_mov_b64 s[4:5], 0x1000
	v_lshl_add_u64 v[16:17], v[20:21], 0, s[4:5]
	s_movk_i32 s4, 0x1000
	v_add_co_u32_e32 v20, vcc, s4, v20
	global_load_dwordx4 v[16:19], v[16:17], off offset:16
	s_nop 0
	v_addc_co_u32_e32 v21, vcc, 0, v21, vcc
	global_load_dwordx4 v[20:23], v[20:21], off
	v_ashrrev_i32_e32 v24, 3, v24
	s_lshl_b32 s3, s3, 5
	v_readlane_b32 s4, v254, 22
	v_lshlrev_b32_e32 v40, 1, v25
	v_and_b32_e32 v26, -8, v24
	s_add_i32 s3, s4, s3
	s_sub_i32 s3, s3, s8
	v_lshl_add_u64 v[24:25], s[0:1], 0, v[40:41]
	s_mov_b64 s[0:1], 0xa1cd000
	v_lshl_add_u64 v[28:29], v[24:25], 0, s[0:1]
	v_add_u32_e32 v40, s3, v26
	v_readlane_b32 s3, v254, 25
	s_sub_i32 s3, s3, s8
	v_readlane_b32 s6, v254, 52
	s_waitcnt vmcnt(5)
	v_mov_b32_e32 v30, v2
	v_mov_b32_e32 v32, v3
	v_mov_b32_e32 v34, v0
	v_mov_b32_e32 v36, v1
	s_waitcnt vmcnt(4)
	v_mov_b32_e32 v38, v6
	v_mov_b32_e32 v42, v7
	v_mov_b32_e32 v44, v4
	v_mov_b32_e32 v46, v5
	s_waitcnt vmcnt(3)
	v_mov_b32_e32 v48, v10
	v_mov_b32_e32 v50, v11
	v_mov_b32_e32 v52, v8
	v_mov_b32_e32 v54, v9
	s_waitcnt vmcnt(2)
	v_mov_b32_e32 v56, v14
	v_mov_b32_e32 v58, v15
	v_mov_b32_e32 v60, v12
	v_mov_b32_e32 v62, v13
	v_mov_b32_e32 v64, v2
	v_mov_b32_e32 v65, v10
	v_mov_b32_e32 v66, v3
	v_mov_b32_e32 v67, v11
	v_mov_b32_e32 v68, v0
	v_mov_b32_e32 v69, v8
	v_mov_b32_e32 v70, v1
	v_mov_b32_e32 v71, v9
	v_mov_b32_e32 v72, v6
	v_mov_b32_e32 v73, v14
	v_mov_b32_e32 v74, v7
	v_mov_b32_e32 v75, v15
	v_mov_b32_e32 v76, v4
	v_mov_b32_e32 v77, v12
	v_mov_b32_e32 v78, v5
	v_mov_b32_e32 v79, v13
	s_waitcnt vmcnt(1)
	v_mov_b32_e32 v31, v18
	v_mov_b32_e32 v33, v19
	v_mov_b32_e32 v35, v16
	v_mov_b32_e32 v37, v17
	s_waitcnt vmcnt(0)
	v_mov_b32_e32 v39, v22
	v_mov_b32_e32 v43, v23
	v_mov_b32_e32 v45, v20
	v_mov_b32_e32 v47, v21
	v_mov_b32_e32 v49, v18
	v_mov_b32_e32 v51, v19
	v_mov_b32_e32 v53, v16
	v_mov_b32_e32 v55, v17
	v_mov_b32_e32 v57, v22
	v_mov_b32_e32 v59, v23
	v_mov_b32_e32 v61, v20
	v_mov_b32_e32 v63, v21
	s_branch .LBB0_311
.LBB0_310:
	s_or_b64 exec, exec, s[0:1]
	global_load_dwordx4 v[24:27], v[114:115], off offset:1024
	v_pk_mul_f32 v[92:93], v[46:47], v[92:93]
	v_pk_mul_f32 v[88:89], v[42:43], v[88:89]
	v_pk_mul_f32 v[86:87], v[34:35], v[86:87]
	v_pk_mul_f32 v[84:85], v[36:37], v[84:85]
	v_pk_mul_f32 v[82:83], v[30:31], v[82:83]
	v_pk_mul_f32 v[80:81], v[32:33], v[80:81]
	v_pk_mul_f32 v[94:95], v[44:45], v[94:95]
	v_pk_mul_f32 v[90:91], v[38:39], v[90:91]
	v_fma_f32 v92, v13, v117, v92
	v_fma_f32 v88, v15, v119, v88
	v_fma_f32 v86, v8, v120, v86
	v_fma_f32 v84, v9, v121, v84
	v_fma_f32 v82, v10, v122, v82
	v_fma_f32 v80, v11, v123, v80
	s_add_i32 s2, s2, s9
	v_fma_f32 v94, v12, v116, v94
	v_fma_f32 v90, v14, v118, v90
	v_add_f32_e32 v92, v92, v93
	v_add_f32_e32 v88, v88, v89
	v_add_f32_e32 v86, v86, v87
	v_add_f32_e32 v84, v84, v85
	v_add_f32_e32 v82, v82, v83
	v_add_f32_e32 v80, v80, v81
	s_cmp_ge_i32 s2, s6
	v_add_f32_e32 v94, v94, v95
	v_add_f32_e32 v90, v90, v91
	v_add_u32_e32 v40, s3, v40
	s_waitcnt vmcnt(0)
	v_lshlrev_b32_e32 v81, 16, v24
	v_and_b32_e32 v24, 0xffff0000, v24
	v_lshlrev_b32_e32 v83, 16, v25
	v_and_b32_e32 v25, 0xffff0000, v25
	v_lshlrev_b32_e32 v85, 16, v26
	v_and_b32_e32 v26, 0xffff0000, v26
	v_lshlrev_b32_e32 v87, 16, v27
	v_and_b32_e32 v27, 0xffff0000, v27
	v_mul_f32_e32 v24, v92, v24
	v_mul_f32_e32 v25, v88, v25
	v_mul_f32_e32 v26, v84, v26
	v_mul_f32_e32 v27, v80, v27
	v_mul_f32_e32 v81, v94, v81
	v_mul_f32_e32 v83, v90, v83
	v_mul_f32_e32 v85, v86, v85
	v_mul_f32_e32 v82, v82, v87
	v_cvt_pk_bf16_f32 v24, v81, v24
	v_cvt_pk_bf16_f32 v25, v83, v25
	v_cvt_pk_bf16_f32 v26, v85, v26
	v_cvt_pk_bf16_f32 v27, v82, v27
	global_store_dwordx4 v[114:115], v[24:27], off
	s_cbranch_scc1 .LBB0_319
